# merge phase: four start groups per XCD (bits 3-4 of block id), 3.5us apart
# speedup vs baseline: 1.0050x; 1.0050x over previous
; __global__ void __launch_bounds__(NTHREADS, 2) fwd_kernel(Args A) {
;     ...
;         case 4: if (PMASK & 16) { pg8::Gemm g{(const bf16_t*)(ws + WS_Y), wl + WT_BR, Mx, DM, DM, 0, 0}; const bool coop = (ph_hi - ph_lo > 1);
;                   if (last) S.init(NLAT, DM, C.G, C.bid); else if (coop) S.init(NLAT, DM, C.G, C.bid, NCTX, 4); else S.init(MROWS, DM, C.G, C.bid);
;                   pg8::EpiMerge E{(const bf16_t*)(ws + WS_G), (bf16_t*)(ws + WS_MB), (float*)(ws + WS_PB)};
;                   pg8::gemm_phase<pg8::EpiMerge, true>(C.lds, C.tid, g, S, E);
.LBB0_242:
	v_readlane_b32 s100, v249, 56
	s_nop 3
	s_bfe_u32 s100, s100, 0x20003
	s_cmp_eq_u32 s100, 0
	s_cbranch_scc1 .Lmerge_nodelay
.Lmerge_delay:
	s_sleep 110
	s_sub_u32 s100, s100, 1
	s_cmp_lg_u32 s100, 0
	s_cbranch_scc1 .Lmerge_delay
